# loop-edge strategy: diff loop gets a straight-line steady-state interval body per role (scalar dispatch, mask/first-tile/overflow paths out of line)
# speedup vs baseline: 1.0081x; 1.0081x over previous
; __device__ __forceinline__ s16x4 vtr(ldsp p) { return __builtin_bit_cast(s16x4, __builtin_amdgcn_ds_read_tr16_b64_v4i16((LAS v4i16_t*)p)); }
; template <bool DIFF>
; __device__ __forceinline__ void attn_unit(const AttnP& A, int b, int h, int qi, ldsp lds) {
;     ...
;     for (int kt = kt0; kt < nt; ++kt) {
;         if (kt + 1 < nt) LOAD_TILE(kt + 1);
;         if (64 * kt <= qmax_w) {
;             ldsp Kb = lds + (kt & 1) * STAGE; ldsp Vb = Kb + 64 * KP;
;             bf16x8 kf[8]; bf16x8 ka0, ka1, qa; f32x16 s0, s1;
;     ...
;             for (int t = 0; t < 2; ++t)
; #pragma unroll
;                 for (int j = 0; j < 4; ++j) {
;                     const bf16x8 vf = (bf16x8){vlo[t * 4 + j][0], vlo[t * 4 + j][1], vlo[t * 4 + j][2], vlo[t * 4 + j][3], vhi[t * 4 + j][0], vhi[t * 4 + j][1], vhi[t * 4 + j][2], vhi[t * 4 + j][3]};
;                     o[t] = __builtin_amdgcn_mfma_f32_32x32x16_bf16(vf, pw[j], o[t], 0, 0, 0);
;                 }
;             if (DIFF) {
; #pragma unroll
;                 for (int t = 2; t < NTD; ++t)
; #pragma unroll
;                     for (int j = 0; j < 4; ++j) { vlo[(t - 2) * 4 + j] = vtr(Vb + trb + (16 * j) * VP + t * 64); vhi[(t - 2) * 4 + j] = vtr(Vb + trb + (16 * j + 8) * VP + t * 64); }
;                 __builtin_amdgcn_sched_barrier(0);
; #pragma unroll
;                 for (int t = 2; t < NTD; ++t)
; #pragma unroll
;                     for (int j = 0; j < 4; ++j) {
;                         const int i = (t - 2) * 4 + j;
;                         const bf16x8 vf = (bf16x8){vlo[i][0], vlo[i][1], vlo[i][2], vlo[i][3], vhi[i][0], vhi[i][1], vhi[i][2], vhi[i][3]};
;                         o[t] = __builtin_amdgcn_mfma_f32_32x32x16_bf16(vf, pw[j], o[t], 0, 0, 0);
;                     }
.Lda_top:
	s_and_b64 vcc, exec, s[16:17]
	s_cbranch_vccz .Lda_gen
	s_cmp_lt_i32 s75, 1
	s_cbranch_scc1 .Lda_gen
	s_add_i32 s0, s31, -3
	s_cmp_gt_i32 s75, s0
	s_cbranch_scc1 .Lda_gen
.Lda_s_top:
	s_bitcmp1_b32 s75, 0
	s_cselect_b32 s45, 0x9500, 0
	s_sub_i32 s71, 0x9500, s45
	v_add_u32_e32 v239, s45, v234
	v_add_u32_e32 v236, s71, v231
	ds_read_b64_tr_b16 v[148:149], v236 offset:17472
	ds_read_b64_tr_b16 v[150:151], v236 offset:20032
	ds_read_b64_tr_b16 v[152:153], v236 offset:17408
	ds_read_b64_tr_b16 v[154:155], v236 offset:19968
	ds_read_b64_tr_b16 v[156:157], v236 offset:22592
	ds_read_b64_tr_b16 v[158:159], v236 offset:25152
	ds_read_b64_tr_b16 v[160:161], v236 offset:22528
	ds_read_b64_tr_b16 v[162:163], v236 offset:25088
	ds_read_b64_tr_b16 v[164:165], v236 offset:27712
	ds_read_b64_tr_b16 v[166:167], v236 offset:30272
	ds_read_b64_tr_b16 v[168:169], v236 offset:27648
	ds_read_b64_tr_b16 v[170:171], v236 offset:30208
	ds_read_b64_tr_b16 v[172:173], v236 offset:32768
	ds_read_b64_tr_b16 v[174:175], v236 offset:35328
	ds_read_b64_tr_b16 v[176:177], v236 offset:32832
	ds_read_b64_tr_b16 v[178:179], v236 offset:35392
	s_waitcnt lgkmcnt(14)
	v_mfma_f32_32x32x16_bf16 v[34:49], v[148:151], v[98:101], v[34:49]
	ds_read_b64_tr_b16 v[90:91], v236 offset:17536
	ds_read_b64_tr_b16 v[92:93], v236 offset:20096
	s_waitcnt lgkmcnt(14)
	v_mfma_f32_32x32x16_bf16 v[50:65], v[152:155], v[98:101], v[50:65]
	ds_read_b64_tr_b16 v[94:95], v236 offset:17600
	ds_read_b64_tr_b16 v[96:97], v236 offset:20160
	s_waitcnt lgkmcnt(14)
	v_mfma_f32_32x32x16_bf16 v[34:49], v[156:159], v[102:105], v[34:49]
	ds_read_b64_tr_b16 v[106:107], v236 offset:22656
	ds_read_b64_tr_b16 v[108:109], v236 offset:25216
	s_waitcnt lgkmcnt(14)
	v_mfma_f32_32x32x16_bf16 v[50:65], v[160:163], v[102:105], v[50:65]
	ds_read_b64_tr_b16 v[110:111], v236 offset:22720
	ds_read_b64_tr_b16 v[112:113], v236 offset:25280
	s_waitcnt lgkmcnt(14)
	v_mfma_f32_32x32x16_bf16 v[34:49], v[164:167], v[82:85], v[34:49]
	ds_read_b64_tr_b16 v[240:241], v236 offset:27776
	ds_read_b64_tr_b16 v[242:243], v236 offset:30336
	s_waitcnt lgkmcnt(14)
	v_mfma_f32_32x32x16_bf16 v[50:65], v[168:171], v[82:85], v[50:65]
	ds_read_b64_tr_b16 v[148:149], v236 offset:27840
	ds_read_b64_tr_b16 v[150:151], v236 offset:30400
	s_waitcnt lgkmcnt(14)
	v_mfma_f32_32x32x16_bf16 v[50:65], v[172:175], v[86:89], v[50:65]
	ds_read_b64_tr_b16 v[152:153], v236 offset:32896
	ds_read_b64_tr_b16 v[154:155], v236 offset:35456
	s_waitcnt lgkmcnt(14)
	v_mfma_f32_32x32x16_bf16 v[34:49], v[176:179], v[86:89], v[34:49]
	ds_read_b64_tr_b16 v[156:157], v236 offset:32960
	ds_read_b64_tr_b16 v[158:159], v236 offset:35520
	s_waitcnt lgkmcnt(14)
	v_mfma_f32_32x32x16_bf16 v[18:33], v[90:93], v[98:101], v[18:33]
	ds_read_b128 v[160:163], v239
	s_waitcnt lgkmcnt(13)
	v_mfma_f32_32x32x16_bf16 v[2:17], v[94:97], v[98:101], v[2:17]
	ds_read_b128 v[164:167], v239 offset:8704
	s_waitcnt lgkmcnt(12)
	v_mfma_f32_32x32x16_bf16 v[18:33], v[106:109], v[102:105], v[18:33]
	ds_read_b128 v[168:171], v239 offset:32
	s_waitcnt lgkmcnt(11)
	v_mfma_f32_32x32x16_bf16 v[2:17], v[110:113], v[102:105], v[2:17]
	ds_read_b128 v[172:175], v239 offset:8736
	s_waitcnt lgkmcnt(10)
	v_mfma_f32_32x32x16_bf16 v[18:33], v[240:243], v[82:85], v[18:33]
	ds_read_b128 v[176:179], v239 offset:64
	s_waitcnt lgkmcnt(9)
	v_mfma_f32_32x32x16_bf16 v[2:17], v[148:151], v[82:85], v[2:17]
	ds_read_b128 v[240:243], v239 offset:8768
	s_waitcnt lgkmcnt(8)
	v_mfma_f32_32x32x16_bf16 v[18:33], v[152:155], v[86:89], v[18:33]
	ds_read_b128 v[148:151], v239 offset:96
	s_waitcnt lgkmcnt(7)
	v_mfma_f32_32x32x16_bf16 v[2:17], v[156:159], v[86:89], v[2:17]
	ds_read_b128 v[152:155], v239 offset:8800
	s_waitcnt lgkmcnt(7)
	v_mfma_f32_32x32x16_bf16 v[98:113], v[160:163], v[116:119], v[66:81]
	s_waitcnt lgkmcnt(6)
	v_mfma_f32_32x32x16_bf16 v[82:97], v[164:167], v[116:119], v[66:81]
	s_waitcnt lgkmcnt(5)
	v_mfma_f32_32x32x16_bf16 v[98:113], v[168:171], v[120:123], v[98:113]
	s_waitcnt lgkmcnt(4)
	v_mfma_f32_32x32x16_bf16 v[82:97], v[172:175], v[120:123], v[82:97]
	s_waitcnt lgkmcnt(3)
	v_mfma_f32_32x32x16_bf16 v[98:113], v[176:179], v[124:127], v[98:113]
	s_waitcnt lgkmcnt(2)
	v_mfma_f32_32x32x16_bf16 v[82:97], v[240:243], v[124:127], v[82:97]
	s_waitcnt lgkmcnt(1)
	v_mfma_f32_32x32x16_bf16 v[98:113], v[148:151], v[128:131], v[98:113]
	s_waitcnt lgkmcnt(0)
	v_mfma_f32_32x32x16_bf16 v[82:97], v[152:155], v[128:131], v[82:97]
	s_waitcnt vmcnt(0)
	v_add_u32_e32 v204, s71, v226
	ds_write_b128 v204, v[132:135]
	v_add_u32_e32 v205, s71, v228
	ds_write_b128 v205, v[140:143]
	v_add_u32_e32 v204, s45, v227
	ds_write_b128 v204, v[136:139] offset:17408
	v_add_u32_e32 v205, s45, v229
	ds_write_b128 v205, v[144:147] offset:17408
	global_load_dwordx4 v[136:139], v[196:197], off offset:2048
	global_load_dwordx4 v[144:147], v[198:199], off offset:2048
	v_lshl_add_u64 v[196:197], v[196:197], 0, s[26:27]
	v_lshl_add_u64 v[198:199], v[198:199], 0, s[26:27]
	global_load_dwordx4 v[132:135], v[196:197], off offset:1024
	global_load_dwordx4 v[140:143], v[198:199], off offset:1024
	v_exp_f32_e32 v148, v98
	v_exp_f32_e32 v164, v82
	v_exp_f32_e32 v149, v99
	v_exp_f32_e32 v165, v83
	v_add_f32_e32 v237, 0, v148
	v_add_f32_e32 v238, 0, v164
	v_exp_f32_e32 v150, v100
	v_exp_f32_e32 v166, v84
	v_add_f32_e32 v237, v149, v237
	v_add_f32_e32 v238, v165, v238
	v_exp_f32_e32 v151, v101
	v_exp_f32_e32 v167, v85
	v_add_f32_e32 v237, v150, v237
	v_add_f32_e32 v238, v166, v238
	v_exp_f32_e32 v152, v102
	v_exp_f32_e32 v168, v86
	v_add_f32_e32 v237, v151, v237
	v_add_f32_e32 v238, v167, v238
	v_exp_f32_e32 v153, v103
	v_exp_f32_e32 v169, v87
	v_add_f32_e32 v237, v152, v237
	v_add_f32_e32 v238, v168, v238
	v_exp_f32_e32 v154, v104
	v_exp_f32_e32 v170, v88
	v_add_f32_e32 v237, v153, v237
	v_add_f32_e32 v238, v169, v238
	v_exp_f32_e32 v155, v105
	v_exp_f32_e32 v171, v89
	v_add_f32_e32 v237, v154, v237
	v_add_f32_e32 v238, v170, v238
	v_exp_f32_e32 v156, v106
	v_exp_f32_e32 v172, v90
	v_add_f32_e32 v237, v155, v237
	v_add_f32_e32 v238, v171, v238
	v_exp_f32_e32 v157, v107
	v_exp_f32_e32 v173, v91
	v_add_f32_e32 v237, v156, v237
	v_add_f32_e32 v238, v172, v238
	v_exp_f32_e32 v158, v108
	v_exp_f32_e32 v174, v92
	v_add_f32_e32 v237, v157, v237
	v_add_f32_e32 v238, v173, v238
	v_exp_f32_e32 v159, v109
	v_exp_f32_e32 v175, v93
	v_add_f32_e32 v237, v158, v237
	v_add_f32_e32 v238, v174, v238
	v_exp_f32_e32 v160, v110
	v_exp_f32_e32 v176, v94
	v_add_f32_e32 v237, v159, v237
	v_add_f32_e32 v238, v175, v238
	v_exp_f32_e32 v161, v111
	v_exp_f32_e32 v177, v95
	v_add_f32_e32 v237, v160, v237
	v_add_f32_e32 v238, v176, v238
	v_exp_f32_e32 v162, v112
	v_exp_f32_e32 v178, v96
	v_add_f32_e32 v237, v161, v237
	v_add_f32_e32 v238, v177, v238
	v_exp_f32_e32 v163, v113
	v_exp_f32_e32 v179, v97
	v_add_f32_e32 v237, v162, v237
	v_add_f32_e32 v238, v178, v238
	s_nop 0
	v_add_f32_e32 v237, v163, v237
	v_add_f32_e32 v238, v179, v238
	v_add_f32_e32 v204, v237, v238
	v_cmp_lt_f32_e32 vcc, s85, v204
	s_cbranch_vccnz .Lda_s_slow
; __device__ __forceinline__ unsigned cvtpk(float lo, float hi) { f32x2 v = {lo, hi}; bf16x2_t b = __builtin_convertvector(v, bf16x2_t); return __builtin_bit_cast(unsigned, b); }
; template <bool DIFF>
; __device__ __forceinline__ void attn_unit(const AttnP& A, int b, int h, int qi, ldsp lds) {
;     ...
;             l_run += psa + psb;
;     ...
;             bf16x8 pw[4];
; #pragma unroll
;             for (int j = 0; j < 4; ++j) {
;                 u32x4 pk;
;                 if (j < 2) { const int rb = 8 * (j & 1); pk.x = cvtpk(s0[rb], s0[rb + 1]); pk.y = cvtpk(s0[rb + 2], s0[rb + 3]); pk.z = cvtpk(s0[rb + 4], s0[rb + 5]); pk.w = cvtpk(s0[rb + 6], s0[rb + 7]); }
;                 else { const int rb = 8 * (j & 1); pk.x = cvtpk(s1[rb], s1[rb + 1]); pk.y = cvtpk(s1[rb + 2], s1[rb + 3]); pk.z = cvtpk(s1[rb + 4], s1[rb + 5]); pk.w = cvtpk(s1[rb + 6], s1[rb + 7]); }
;                 pw[j] = __builtin_bit_cast(bf16x8, pk);
;             }
;     ...
;         if (kt + 1 < nt) STORE_TILE((kt + 1) & 1);
;         __syncthreads();
	v_cvt_pk_bf16_f32 v98, v148, v149
	v_cvt_pk_bf16_f32 v99, v150, v151
	v_cvt_pk_bf16_f32 v100, v152, v153
	v_cvt_pk_bf16_f32 v101, v154, v155
	v_cvt_pk_bf16_f32 v102, v156, v157
	v_cvt_pk_bf16_f32 v103, v158, v159
	v_cvt_pk_bf16_f32 v104, v160, v161
	v_cvt_pk_bf16_f32 v105, v162, v163
	v_cvt_pk_bf16_f32 v82, v164, v165
	v_cvt_pk_bf16_f32 v83, v166, v167
	v_cvt_pk_bf16_f32 v84, v168, v169
	v_cvt_pk_bf16_f32 v85, v170, v171
	v_cvt_pk_bf16_f32 v86, v172, v173
	v_cvt_pk_bf16_f32 v87, v174, v175
	v_cvt_pk_bf16_f32 v88, v176, v177
	v_cvt_pk_bf16_f32 v89, v178, v179
	v_add_f32_e32 v230, v204, v230
	s_waitcnt lgkmcnt(0)
	s_barrier
	s_add_i32 s75, s75, 1
	s_add_i32 s74, s74, 64
	s_add_i32 s0, s31, -3
	s_cmp_le_i32 s75, s0
	s_cbranch_scc1 .Lda_s_top

; __device__ __forceinline__ s16x4 vtr(ldsp p) { return __builtin_bit_cast(s16x4, __builtin_amdgcn_ds_read_tr16_b64_v4i16((LAS v4i16_t*)p)); }
; #define MASK_BLOCK() do { if (kt == 0 || kt >= diag0) { \
;             _Pragma("unroll") for (int r = 0; r < 16; ++r) { const int kpp = 64 * kt + crow(r, hi); \
;                 if (kpp < 48 || kpp > q_pp) s0[r] = -INFINITY; \
;                 if (kpp + 32 < 48 || kpp + 32 > q_pp) s1[r] = -INFINITY; } } } while (0)
; #define EXPSUM_BLOCK() do { psa = 0.f; psb = 0.f; \
;             _Pragma("unroll") for (int r = 0; r < 16; ++r) { s0[r] = __builtin_amdgcn_exp2f(s0[r]); s1[r] = __builtin_amdgcn_exp2f(s1[r]); psa += s0[r]; asm("" : "+v"(psa)); psb += s1[r]; asm("" : "+v"(psb)); } } while (0)
; template <bool DIFF>
; __device__ __forceinline__ void attn_unit(const AttnP& A, int b, int h, int qi, ldsp lds) {
;     ...
;             QK_BLOCK();
;             s16x4 vlo[8], vhi[8];
; #pragma unroll
;             for (int t = 0; t < 2; ++t)
; #pragma unroll
;                 for (int j = 0; j < 4; ++j) { vlo[t * 4 + j] = vtr(Vb + trb + (16 * j) * VP + t * 64); vhi[t * 4 + j] = vtr(Vb + trb + (16 * j + 8) * VP + t * 64); }
;             __builtin_amdgcn_sched_barrier(0);
;             MASK_BLOCK();
;             bool full = (kt == kt0);
;             float psa, psb;
;             if (!full) {
;                 EXPSUM_BLOCK();
;                 if (__any(psa + psb > 1.0e18f)) { full = true; QK_BLOCK();
; #pragma unroll
;                     for (int t = 0; t < 2; ++t)
; #pragma unroll
;                         for (int j = 0; j < 4; ++j) { vlo[t * 4 + j] = vtr(Vb + trb + (16 * j) * VP + t * 64); vhi[t * 4 + j] = vtr(Vb + trb + (16 * j + 8) * VP + t * 64); }
;                     MASK_BLOCK(); }
;             }
.Lda_s_slow:
	s_mov_b64 s[48:49], -1
	s_branch .Lda5_full
.Ldb_top:
	s_and_b64 vcc, exec, s[16:17]
	s_cbranch_vccz .Ldb_gen
	s_cmp_lt_i32 s75, 2
	s_cbranch_scc1 .Ldb_gen
	s_add_i32 s0, s31, -2
	s_cmp_gt_i32 s75, s0
	s_cbranch_scc1 .Ldb_gen
.Ldb_s_top:
	s_bitcmp1_b32 s75, 0
	s_cselect_b32 s45, 0x9500, 0
	s_sub_i32 s71, 0x9500, s45
	v_exp_f32_e32 v148, v98
	v_exp_f32_e32 v164, v82
	v_exp_f32_e32 v149, v99
	v_exp_f32_e32 v165, v83
	v_add_f32_e32 v237, 0, v148
	v_add_f32_e32 v238, 0, v164
	v_exp_f32_e32 v150, v100
	v_exp_f32_e32 v166, v84
	v_add_f32_e32 v237, v149, v237
	v_add_f32_e32 v238, v165, v238
	v_exp_f32_e32 v151, v101
	v_exp_f32_e32 v167, v85
	v_add_f32_e32 v237, v150, v237
	v_add_f32_e32 v238, v166, v238
	v_exp_f32_e32 v152, v102
	v_exp_f32_e32 v168, v86
	v_add_f32_e32 v237, v151, v237
	v_add_f32_e32 v238, v167, v238
	v_exp_f32_e32 v153, v103
	v_exp_f32_e32 v169, v87
	v_add_f32_e32 v237, v152, v237
	v_add_f32_e32 v238, v168, v238
	v_exp_f32_e32 v154, v104
	v_exp_f32_e32 v170, v88
	v_add_f32_e32 v237, v153, v237
	v_add_f32_e32 v238, v169, v238
	v_exp_f32_e32 v155, v105
	v_exp_f32_e32 v171, v89
	v_add_f32_e32 v237, v154, v237
	v_add_f32_e32 v238, v170, v238
	v_exp_f32_e32 v156, v106
	v_exp_f32_e32 v172, v90
	v_add_f32_e32 v237, v155, v237
	v_add_f32_e32 v238, v171, v238
	v_exp_f32_e32 v157, v107
	v_exp_f32_e32 v173, v91
	v_add_f32_e32 v237, v156, v237
	v_add_f32_e32 v238, v172, v238
	v_exp_f32_e32 v158, v108
	v_exp_f32_e32 v174, v92
	v_add_f32_e32 v237, v157, v237
	v_add_f32_e32 v238, v173, v238
	v_exp_f32_e32 v159, v109
	v_exp_f32_e32 v175, v93
	v_add_f32_e32 v237, v158, v237
	v_add_f32_e32 v238, v174, v238
	v_exp_f32_e32 v160, v110
	v_exp_f32_e32 v176, v94
	v_add_f32_e32 v237, v159, v237
	v_add_f32_e32 v238, v175, v238
	v_exp_f32_e32 v161, v111
	v_exp_f32_e32 v177, v95
	v_add_f32_e32 v237, v160, v237
	v_add_f32_e32 v238, v176, v238
	v_exp_f32_e32 v162, v112
	v_exp_f32_e32 v178, v96
	v_add_f32_e32 v237, v161, v237
	v_add_f32_e32 v238, v177, v238
	v_exp_f32_e32 v163, v113
	v_exp_f32_e32 v179, v97
	v_add_f32_e32 v237, v162, v237
	v_add_f32_e32 v238, v178, v238
	s_nop 0
	v_add_f32_e32 v237, v163, v237
	v_add_f32_e32 v238, v179, v238
	v_add_f32_e32 v204, v237, v238
	v_cmp_lt_f32_e32 vcc, s85, v204
	s_cbranch_vccnz .Ldb_s_slow
; __device__ __forceinline__ unsigned cvtpk(float lo, float hi) { f32x2 v = {lo, hi}; bf16x2_t b = __builtin_convertvector(v, bf16x2_t); return __builtin_bit_cast(unsigned, b); }
; template <bool DIFF>
; __device__ __forceinline__ void attn_unit(const AttnP& A, int b, int h, int qi, ldsp lds) {
;     ...
;             bf16x8 pw[4];
; #pragma unroll
;             for (int j = 0; j < 4; ++j) {
;                 u32x4 pk;
;                 if (j < 2) { const int rb = 8 * (j & 1); pk.x = cvtpk(s0[rb], s0[rb + 1]); pk.y = cvtpk(s0[rb + 2], s0[rb + 3]); pk.z = cvtpk(s0[rb + 4], s0[rb + 5]); pk.w = cvtpk(s0[rb + 6], s0[rb + 7]); }
;                 else { const int rb = 8 * (j & 1); pk.x = cvtpk(s1[rb], s1[rb + 1]); pk.y = cvtpk(s1[rb + 2], s1[rb + 3]); pk.z = cvtpk(s1[rb + 4], s1[rb + 5]); pk.w = cvtpk(s1[rb + 6], s1[rb + 7]); }
;                 pw[j] = __builtin_bit_cast(bf16x8, pk);
;             }
;             __builtin_amdgcn_sched_barrier(0);
;             __builtin_amdgcn_s_setprio(1);
; #pragma unroll
;             for (int t = 0; t < 2; ++t)
; #pragma unroll
;                 for (int j = 0; j < 4; ++j) {
;                     const bf16x8 vf = (bf16x8){vlo[t * 4 + j][0], vlo[t * 4 + j][1], vlo[t * 4 + j][2], vlo[t * 4 + j][3], vhi[t * 4 + j][0], vhi[t * 4 + j][1], vhi[t * 4 + j][2], vhi[t * 4 + j][3]};
;                     o[t] = __builtin_amdgcn_mfma_f32_32x32x16_bf16(vf, pw[j], o[t], 0, 0, 0);
;                 }
;             if (DIFF) {
; #pragma unroll
;                 for (int t = 2; t < NTD; ++t)
; #pragma unroll
;                     for (int j = 0; j < 4; ++j) { vlo[(t - 2) * 4 + j] = vtr(Vb + trb + (16 * j) * VP + t * 64); vhi[(t - 2) * 4 + j] = vtr(Vb + trb + (16 * j + 8) * VP + t * 64); }
;                 __builtin_amdgcn_sched_barrier(0);
; #pragma unroll
;                 for (int t = 2; t < NTD; ++t)
; #pragma unroll
;                     for (int j = 0; j < 4; ++j) {
;                         const int i = (t - 2) * 4 + j;
;                         const bf16x8 vf = (bf16x8){vlo[i][0], vlo[i][1], vlo[i][2], vlo[i][3], vhi[i][0], vhi[i][1], vhi[i][2], vhi[i][3]};
;                         o[t] = __builtin_amdgcn_mfma_f32_32x32x16_bf16(vf, pw[j], o[t], 0, 0, 0);
;                     }
;             }
;             __builtin_amdgcn_s_setprio(0);
;         }
;         if (kt + 1 < nt) STORE_TILE((kt + 1) & 1);
;         __syncthreads();
	v_add_u32_e32 v239, s45, v234
	v_add_u32_e32 v236, s71, v231
	ds_read_b64_tr_b16 v[90:91], v236 offset:17472
	ds_read_b64_tr_b16 v[92:93], v236 offset:20032
	ds_read_b64_tr_b16 v[94:95], v236 offset:17408
	ds_read_b64_tr_b16 v[96:97], v236 offset:19968
	ds_read_b64_tr_b16 v[106:107], v236 offset:22592
	ds_read_b64_tr_b16 v[108:109], v236 offset:25152
	ds_read_b64_tr_b16 v[110:111], v236 offset:22528
	ds_read_b64_tr_b16 v[112:113], v236 offset:25088
	ds_read_b64_tr_b16 v[240:241], v236 offset:27712
	ds_read_b64_tr_b16 v[242:243], v236 offset:30272
	v_cvt_pk_bf16_f32 v98, v148, v149
	v_cvt_pk_bf16_f32 v99, v150, v151
	v_cvt_pk_bf16_f32 v100, v152, v153
	v_cvt_pk_bf16_f32 v101, v154, v155
	v_cvt_pk_bf16_f32 v102, v156, v157
	v_cvt_pk_bf16_f32 v103, v158, v159
	v_cvt_pk_bf16_f32 v104, v160, v161
	v_cvt_pk_bf16_f32 v105, v162, v163
	v_cvt_pk_bf16_f32 v82, v164, v165
	v_cvt_pk_bf16_f32 v83, v166, v167
	v_cvt_pk_bf16_f32 v84, v168, v169
	v_cvt_pk_bf16_f32 v85, v170, v171
	v_cvt_pk_bf16_f32 v86, v172, v173
	v_cvt_pk_bf16_f32 v87, v174, v175
	v_cvt_pk_bf16_f32 v88, v176, v177
	v_cvt_pk_bf16_f32 v89, v178, v179
	v_add_f32_e32 v230, v204, v230
	ds_read_b64_tr_b16 v[148:149], v236 offset:27648
	ds_read_b64_tr_b16 v[150:151], v236 offset:30208
	ds_read_b64_tr_b16 v[152:153], v236 offset:32768
	ds_read_b64_tr_b16 v[154:155], v236 offset:35328
	ds_read_b64_tr_b16 v[156:157], v236 offset:32832
	ds_read_b64_tr_b16 v[158:159], v236 offset:35392
	s_setprio 1
	s_waitcnt lgkmcnt(14)
	v_mfma_f32_32x32x16_bf16 v[34:49], v[90:93], v[98:101], v[34:49]
	ds_read_b64_tr_b16 v[160:161], v236 offset:17536
	ds_read_b64_tr_b16 v[162:163], v236 offset:20096
	s_waitcnt lgkmcnt(14)
	v_mfma_f32_32x32x16_bf16 v[50:65], v[94:97], v[98:101], v[50:65]
	ds_read_b64_tr_b16 v[164:165], v236 offset:17600
	ds_read_b64_tr_b16 v[166:167], v236 offset:20160
	s_waitcnt lgkmcnt(14)
	v_mfma_f32_32x32x16_bf16 v[34:49], v[106:109], v[102:105], v[34:49]
	ds_read_b64_tr_b16 v[168:169], v236 offset:22656
	ds_read_b64_tr_b16 v[170:171], v236 offset:25216
	s_waitcnt lgkmcnt(14)
	v_mfma_f32_32x32x16_bf16 v[50:65], v[110:113], v[102:105], v[50:65]
	ds_read_b64_tr_b16 v[172:173], v236 offset:22720
	ds_read_b64_tr_b16 v[174:175], v236 offset:25280
	s_waitcnt lgkmcnt(14)
	v_mfma_f32_32x32x16_bf16 v[34:49], v[240:243], v[82:85], v[34:49]
	ds_read_b64_tr_b16 v[176:177], v236 offset:27776
	ds_read_b64_tr_b16 v[178:179], v236 offset:30336
	s_waitcnt lgkmcnt(14)
	v_mfma_f32_32x32x16_bf16 v[50:65], v[148:151], v[82:85], v[50:65]
	ds_read_b64_tr_b16 v[90:91], v236 offset:27840
	ds_read_b64_tr_b16 v[92:93], v236 offset:30400
	s_waitcnt lgkmcnt(14)
	v_mfma_f32_32x32x16_bf16 v[50:65], v[152:155], v[86:89], v[50:65]
	ds_read_b64_tr_b16 v[94:95], v236 offset:32896
	ds_read_b64_tr_b16 v[96:97], v236 offset:35456
	s_waitcnt lgkmcnt(14)
	v_mfma_f32_32x32x16_bf16 v[34:49], v[156:159], v[86:89], v[34:49]
	ds_read_b64_tr_b16 v[106:107], v236 offset:32960
	ds_read_b64_tr_b16 v[108:109], v236 offset:35520
	s_waitcnt lgkmcnt(14)
	v_mfma_f32_32x32x16_bf16 v[18:33], v[160:163], v[98:101], v[18:33]
	ds_read_b128 v[240:243], v239
	s_waitcnt lgkmcnt(13)
	v_mfma_f32_32x32x16_bf16 v[2:17], v[164:167], v[98:101], v[2:17]
	ds_read_b128 v[148:151], v239 offset:8704
	s_waitcnt lgkmcnt(12)
	v_mfma_f32_32x32x16_bf16 v[18:33], v[168:171], v[102:105], v[18:33]
	ds_read_b128 v[152:155], v239 offset:32
	s_waitcnt lgkmcnt(11)
	v_mfma_f32_32x32x16_bf16 v[2:17], v[172:175], v[102:105], v[2:17]
	ds_read_b128 v[156:159], v239 offset:8736
	s_waitcnt lgkmcnt(10)
	v_mfma_f32_32x32x16_bf16 v[18:33], v[176:179], v[82:85], v[18:33]
	ds_read_b128 v[160:163], v239 offset:64
	s_waitcnt lgkmcnt(9)
	v_mfma_f32_32x32x16_bf16 v[2:17], v[90:93], v[82:85], v[2:17]
	ds_read_b128 v[164:167], v239 offset:8768
	s_waitcnt lgkmcnt(8)
	v_mfma_f32_32x32x16_bf16 v[18:33], v[94:97], v[86:89], v[18:33]
	ds_read_b128 v[168:171], v239 offset:96
	s_waitcnt lgkmcnt(7)
	v_mfma_f32_32x32x16_bf16 v[2:17], v[106:109], v[86:89], v[2:17]
	ds_read_b128 v[172:175], v239 offset:8800
	s_waitcnt lgkmcnt(7)
	v_mfma_f32_32x32x16_bf16 v[98:113], v[240:243], v[116:119], v[66:81]
	s_waitcnt lgkmcnt(6)
	v_mfma_f32_32x32x16_bf16 v[82:97], v[148:151], v[116:119], v[66:81]
	s_waitcnt lgkmcnt(5)
	v_mfma_f32_32x32x16_bf16 v[98:113], v[152:155], v[120:123], v[98:113]
	s_waitcnt lgkmcnt(4)
	v_mfma_f32_32x32x16_bf16 v[82:97], v[156:159], v[120:123], v[82:97]
	s_waitcnt lgkmcnt(3)
	v_mfma_f32_32x32x16_bf16 v[98:113], v[160:163], v[124:127], v[98:113]
	s_waitcnt lgkmcnt(2)
	v_mfma_f32_32x32x16_bf16 v[82:97], v[164:167], v[124:127], v[82:97]
	s_waitcnt lgkmcnt(1)
	v_mfma_f32_32x32x16_bf16 v[98:113], v[168:171], v[128:131], v[98:113]
	s_waitcnt lgkmcnt(0)
	v_mfma_f32_32x32x16_bf16 v[82:97], v[172:175], v[128:131], v[82:97]
	s_setprio 0
	s_waitcnt vmcnt(0)
	v_add_u32_e32 v204, s71, v226
	ds_write_b128 v204, v[132:135]
	v_add_u32_e32 v205, s71, v228
	ds_write_b128 v205, v[140:143]
	v_add_u32_e32 v204, s45, v227
	ds_write_b128 v204, v[136:139] offset:17408
	v_add_u32_e32 v205, s45, v229
	ds_write_b128 v205, v[144:147] offset:17408
	global_load_dwordx4 v[136:139], v[196:197], off offset:2048
	global_load_dwordx4 v[144:147], v[198:199], off offset:2048
	v_lshl_add_u64 v[196:197], v[196:197], 0, s[26:27]
	v_lshl_add_u64 v[198:199], v[198:199], 0, s[26:27]
	global_load_dwordx4 v[132:135], v[196:197], off offset:1024
	global_load_dwordx4 v[140:143], v[198:199], off offset:1024
	s_waitcnt lgkmcnt(0)
	s_barrier
	s_add_i32 s75, s75, 1
	s_add_i32 s74, s74, 64
	s_add_i32 s0, s31, -2
	s_cmp_le_i32 s75, s0
	s_cbranch_scc1 .Ldb_s_top
